# attention PV segment: softmax VALU dealt between the MFMAs by issue cost (transcendental 2, other 1) instead of by count
# speedup vs baseline: 1.0002x; 1.0002x over previous
; #define MFMA16(a, b, c) __builtin_amdgcn_mfma_f32_16x16x32_bf16((a), (b), (c), 0, 0, 0)
; DI unsigned pack2(float a, float b) { f32v2_t v = {a, b}; bf16v2_t r = __builtin_convertvector(v, bf16v2_t); return __builtin_bit_cast(unsigned, r); }
; DI void attn_item(const Params& p, int l, bool isS, int b, int h, int cp, char* smem) {
;     ...
;   auto softmax_tile = [&](f32x4 (&st)[2][4], bf16x8 (&pfn)[2][2], float (&alpha)[2], float (&psum)[2], bool (&moved)[2]) {
; #pragma unroll
;     for (int mp = 0; mp < 2; ++mp) {
;       float mx = -INFINITY;
; #pragma unroll
;       for (int mt = 0; mt < 4; ++mt)
; #pragma unroll
;         for (int j = 0; j < 4; ++j) mx = fmaxf(mx, st[mp][mt][j]);
;       mx = quad_max(mx);
;       const float mold = mrun[mp];
;       const float mnew = fmaxf(mold, mx);
;       mrun[mp] = mnew;
;       float ps = 0.f;
; #pragma unroll
;       for (int mt = 0; mt < 4; ++mt)
; #pragma unroll
;         for (int j = 0; j < 4; ++j) { float e = __builtin_amdgcn_exp2f(st[mp][mt][j] - mnew); st[mp][mt][j] = e; ps += e; }
;       psum[mp] = ps;
;       moved[mp] = __any(mnew > mold);
;       alpha[mp] = __builtin_amdgcn_exp2f(mold - mnew);
; #pragma unroll
;       for (int s = 0; s < 2; ++s) {
;         uint4 u = {pack2(st[mp][2 * s][0], st[mp][2 * s][1]), pack2(st[mp][2 * s][2], st[mp][2 * s][3]),
;                    pack2(st[mp][2 * s + 1][0], st[mp][2 * s + 1][1]), pack2(st[mp][2 * s + 1][2], st[mp][2 * s + 1][3])};
;         pfn[mp][s] = __builtin_bit_cast(bf16x8, u);
;       }
;     }
;     ...
;     auto pv_tile = [&]() {
;       const char* Vb = Vs + (j & 1) * 16384;
; #pragma unroll
;       for (int nh = 0; nh < 2; ++nh) {
;         bf16x8 vf[4][2];
; #pragma unroll
;         for (int n = 0; n < 4; ++n) {
;           const int vd = (nh * 4 + n) * 16 + fr;
; #pragma unroll
;           for (int s = 0; s < 2; ++s) vf[n][s] = *(const bf16x8*)(Vb + vd * 128 + (((s * 4 + fq) ^ ((vd >> 1) & 7)) << 4));
;         }
; #pragma unroll
;         for (int n = 0; n < 4; ++n)
; #pragma unroll
;           for (int s = 0; s < 2; ++s) {
;             ot[0][nh * 4 + n] = MFMA16(vf[n][s], pf[0][s], ot[0][nh * 4 + n]);
;             ot[1][nh * 4 + n] = MFMA16(vf[n][s], pf[1][s], ot[1][nh * 4 + n]);
;           }
;       }
.Lat_nomask:
	s_mov_b32 s20, 0xff800000
	s_waitcnt lgkmcnt(14)
	v_mfma_f32_16x16x32_bf16 v[72:75], v[154:157], v[84:87], v[72:75]
	ds_read_b128 v[238:241], v245 offset:47104
	v_max3_f32 v246, v124, s20, v125
	v_max3_f32 v246, v246, v126, v127
	v_max3_f32 v246, v246, v120, v121
	v_max3_f32 v246, v246, v122, v123
	v_max3_f32 v246, v246, v112, v113
	s_waitcnt lgkmcnt(14)
	v_mfma_f32_16x16x32_bf16 v[68:71], v[154:157], v[92:95], v[68:71]
	v_max3_f32 v246, v246, v114, v115
	v_max3_f32 v246, v246, v116, v117
	v_max3_f32 v246, v246, v118, v119
	v_mov_b32_e32 v248, v246
	s_nop 1
	v_permlane16_swap_b32_e32 v246, v248
	v_mfma_f32_16x16x32_bf16 v[72:75], v[158:161], v[88:91], v[72:75]
	v_max_f32_e32 v246, v246, v248
	v_mov_b32_e32 v248, v246
	s_nop 1
	v_permlane32_swap_b32_e32 v246, v248
	v_max3_f32 v246, v153, v246, v248
	v_cmp_gt_f32_e64 s[36:37], v246, v153
	v_mfma_f32_16x16x32_bf16 v[68:71], v[158:161], v[96:99], v[68:71]
	v_max3_f32 v247, v104, s20, v105
	v_max3_f32 v247, v247, v106, v107
	v_max3_f32 v247, v247, v108, v109
	v_max3_f32 v247, v247, v110, v111
	v_max3_f32 v247, v247, v100, v101
	s_waitcnt lgkmcnt(12)
	v_mfma_f32_16x16x32_bf16 v[60:63], v[162:165], v[84:87], v[60:63]
	v_max3_f32 v247, v247, v102, v103
	v_max3_f32 v247, v247, v128, v129
	v_max3_f32 v247, v247, v130, v131
	v_mov_b32_e32 v248, v247
	v_mfma_f32_16x16x32_bf16 v[64:67], v[162:165], v[92:95], v[64:67]
	s_nop 0
	v_permlane16_swap_b32_e32 v247, v248
	v_max_f32_e32 v247, v247, v248
	v_mov_b32_e32 v248, v247
	s_nop 1
	v_permlane32_swap_b32_e32 v247, v248
	v_max3_f32 v247, v152, v247, v248
	v_mfma_f32_16x16x32_bf16 v[60:63], v[166:169], v[88:91], v[60:63]
	v_cmp_gt_f32_e64 s[40:41], v247, v152
	v_sub_f32_e32 v124, v124, v246
	v_exp_f32_e32 v124, v124
	v_sub_f32_e32 v125, v125, v246
	v_mfma_f32_16x16x32_bf16 v[64:67], v[166:169], v[96:99], v[64:67]
	v_exp_f32_e32 v125, v125
	v_sub_f32_e32 v126, v126, v246
	v_exp_f32_e32 v126, v126
	s_waitcnt lgkmcnt(10)
	v_mfma_f32_16x16x32_bf16 v[52:55], v[176:179], v[84:87], v[52:55]
	v_add_f32_e32 v249, v124, v125
	v_sub_f32_e32 v127, v127, v246
	v_exp_f32_e32 v127, v127
	v_add_f32_e32 v249, v126, v249
	v_mfma_f32_16x16x32_bf16 v[56:59], v[176:179], v[92:95], v[56:59]
	v_sub_f32_e32 v120, v120, v246
	v_exp_f32_e32 v120, v120
	v_add_f32_e32 v249, v127, v249
	v_sub_f32_e32 v121, v121, v246
	v_mfma_f32_16x16x32_bf16 v[52:55], v[180:183], v[88:91], v[52:55]
	v_exp_f32_e32 v121, v121
	v_add_f32_e32 v249, v120, v249
	v_sub_f32_e32 v122, v122, v246
	v_mfma_f32_16x16x32_bf16 v[56:59], v[180:183], v[96:99], v[56:59]
	v_exp_f32_e32 v122, v122
	v_add_f32_e32 v249, v121, v249
	v_sub_f32_e32 v123, v123, v246
	v_exp_f32_e32 v123, v123
	s_waitcnt lgkmcnt(8)
	v_mfma_f32_16x16x32_bf16 v[48:51], v[198:201], v[84:87], v[48:51]
	v_add_f32_e32 v249, v122, v249
	v_sub_f32_e32 v112, v112, v246
	v_exp_f32_e32 v112, v112
	v_mfma_f32_16x16x32_bf16 v[24:27], v[198:201], v[92:95], v[24:27]
	v_add_f32_e32 v249, v123, v249
	v_sub_f32_e32 v113, v113, v246
	v_exp_f32_e32 v113, v113
	v_add_f32_e32 v249, v112, v249
	v_mfma_f32_16x16x32_bf16 v[48:51], v[202:205], v[88:91], v[48:51]
	v_sub_f32_e32 v114, v114, v246
	v_exp_f32_e32 v114, v114
	v_add_f32_e32 v249, v113, v249
	v_sub_f32_e32 v115, v115, v246
	v_mfma_f32_16x16x32_bf16 v[24:27], v[202:205], v[96:99], v[24:27]
	v_exp_f32_e32 v115, v115
	v_add_f32_e32 v249, v114, v249
	v_sub_f32_e32 v116, v116, v246
	s_waitcnt lgkmcnt(6)
	v_mfma_f32_16x16x32_bf16 v[40:43], v[206:209], v[84:87], v[40:43]
	v_exp_f32_e32 v116, v116
	v_add_f32_e32 v249, v115, v249
	v_sub_f32_e32 v117, v117, v246
	v_exp_f32_e32 v117, v117
	v_mfma_f32_16x16x32_bf16 v[44:47], v[206:209], v[92:95], v[44:47]
	v_add_f32_e32 v249, v116, v249
	v_sub_f32_e32 v118, v118, v246
	v_exp_f32_e32 v118, v118
	v_add_f32_e32 v249, v117, v249
	v_mfma_f32_16x16x32_bf16 v[40:43], v[214:217], v[88:91], v[40:43]
	v_sub_f32_e32 v119, v119, v246
	v_exp_f32_e32 v119, v119
	v_add_f32_e32 v249, v118, v249
	v_add_f32_e32 v249, v119, v249
	v_mfma_f32_16x16x32_bf16 v[44:47], v[214:217], v[96:99], v[44:47]
	v_sub_f32_e32 v104, v104, v247
	v_exp_f32_e32 v104, v104
	v_sub_f32_e32 v105, v105, v247
	s_waitcnt lgkmcnt(4)
	v_mfma_f32_16x16x32_bf16 v[36:39], v[218:221], v[84:87], v[36:39]
	v_exp_f32_e32 v105, v105
	v_sub_f32_e32 v106, v106, v247
	v_exp_f32_e32 v106, v106
	v_mfma_f32_16x16x32_bf16 v[32:35], v[218:221], v[92:95], v[32:35]
	v_add_f32_e32 v248, v104, v105
	v_sub_f32_e32 v107, v107, v247
	v_exp_f32_e32 v107, v107
	v_add_f32_e32 v248, v106, v248
	v_mfma_f32_16x16x32_bf16 v[36:39], v[222:225], v[88:91], v[36:39]
	v_sub_f32_e32 v108, v108, v247
	v_exp_f32_e32 v108, v108
	v_add_f32_e32 v248, v107, v248
	v_sub_f32_e32 v109, v109, v247
	v_mfma_f32_16x16x32_bf16 v[32:35], v[222:225], v[96:99], v[32:35]
	v_exp_f32_e32 v109, v109
	v_add_f32_e32 v248, v108, v248
	v_sub_f32_e32 v110, v110, v247
	s_waitcnt lgkmcnt(2)
	v_mfma_f32_16x16x32_bf16 v[20:23], v[226:229], v[84:87], v[20:23]
	v_exp_f32_e32 v110, v110
	v_add_f32_e32 v248, v109, v248
	v_sub_f32_e32 v111, v111, v247
	v_exp_f32_e32 v111, v111
	v_mfma_f32_16x16x32_bf16 v[28:31], v[226:229], v[92:95], v[28:31]
	v_add_f32_e32 v248, v110, v248
	v_sub_f32_e32 v100, v100, v247
	v_exp_f32_e32 v100, v100
	v_add_f32_e32 v248, v111, v248
	v_mfma_f32_16x16x32_bf16 v[20:23], v[230:233], v[88:91], v[20:23]
	v_sub_f32_e32 v101, v101, v247
	v_exp_f32_e32 v101, v101
	v_add_f32_e32 v248, v100, v248
	v_sub_f32_e32 v102, v102, v247
	v_mfma_f32_16x16x32_bf16 v[28:31], v[230:233], v[96:99], v[28:31]
	v_exp_f32_e32 v102, v102
	v_add_f32_e32 v248, v101, v248
	v_sub_f32_e32 v103, v103, v247
	s_waitcnt lgkmcnt(0)
	v_mfma_f32_16x16x32_bf16 v[76:79], v[234:237], v[84:87], v[76:79]
	v_exp_f32_e32 v103, v103
	v_add_f32_e32 v248, v102, v248
	v_sub_f32_e32 v128, v128, v247
	v_mfma_f32_16x16x32_bf16 v[80:83], v[234:237], v[92:95], v[80:83]
	v_exp_f32_e32 v128, v128
	v_add_f32_e32 v248, v103, v248
	v_sub_f32_e32 v129, v129, v247
	v_exp_f32_e32 v129, v129
	v_mfma_f32_16x16x32_bf16 v[76:79], v[238:241], v[88:91], v[76:79]
	v_add_f32_e32 v248, v128, v248
	v_sub_f32_e32 v130, v130, v247
	v_exp_f32_e32 v130, v130
	v_add_f32_e32 v248, v129, v248
	v_mfma_f32_16x16x32_bf16 v[80:83], v[238:241], v[96:99], v[80:83]
	v_sub_f32_e32 v131, v131, v247
	v_exp_f32_e32 v131, v131
	v_add_f32_e32 v248, v130, v248
	v_add_f32_e32 v248, v131, v248
	v_cvt_pk_bf16_f32 v84, v124, v125
	v_cvt_pk_bf16_f32 v85, v126, v127
	v_cvt_pk_bf16_f32 v86, v120, v121
	v_cvt_pk_bf16_f32 v87, v122, v123
	v_cvt_pk_bf16_f32 v88, v112, v113
	v_cvt_pk_bf16_f32 v89, v114, v115
	v_cvt_pk_bf16_f32 v90, v116, v117
	v_cvt_pk_bf16_f32 v91, v118, v119
	v_cvt_pk_bf16_f32 v92, v104, v105
	v_cvt_pk_bf16_f32 v93, v106, v107
	v_cvt_pk_bf16_f32 v94, v108, v109
	v_cvt_pk_bf16_f32 v95, v110, v111
	v_cvt_pk_bf16_f32 v96, v100, v101
	v_cvt_pk_bf16_f32 v97, v102, v103
	v_cvt_pk_bf16_f32 v98, v128, v129
	v_cvt_pk_bf16_f32 v99, v130, v131
	s_cmp_eq_u64 s[36:37], 0
	s_cbranch_scc1 .Lat_nors0
; DI void attn_item(const Params& p, int l, bool isS, int b, int h, int cp, char* smem) {
;     ...
;   auto apply_scale = [&](const float (&alpha)[2], const float (&psum)[2], const bool (&moved)[2]) {
; #pragma unroll
;     for (int mp = 0; mp < 2; ++mp) {
;       if (moved[mp]) {
;         lrun[mp] *= alpha[mp];
; #pragma unroll
;         for (int n = 0; n < 8; ++n) { ot[mp][n][0] *= alpha[mp]; ot[mp][n][1] *= alpha[mp]; ot[mp][n][2] *= alpha[mp]; ot[mp][n][3] *= alpha[mp]; }
;       }
;       lrun[mp] += psum[mp];
	v_sub_f32_e32 v244, v153, v246
	v_exp_f32_e32 v244, v244
	s_nop 0
	v_mul_f32_e32 v1, v1, v244
	v_pk_mul_f32 v[72:73], v[72:73], v[244:245] op_sel_hi:[1,0]
	v_pk_mul_f32 v[74:75], v[74:75], v[244:245] op_sel_hi:[1,0]
	v_pk_mul_f32 v[60:61], v[60:61], v[244:245] op_sel_hi:[1,0]
	v_pk_mul_f32 v[62:63], v[62:63], v[244:245] op_sel_hi:[1,0]
	v_pk_mul_f32 v[52:53], v[52:53], v[244:245] op_sel_hi:[1,0]
	v_pk_mul_f32 v[54:55], v[54:55], v[244:245] op_sel_hi:[1,0]
	v_pk_mul_f32 v[48:49], v[48:49], v[244:245] op_sel_hi:[1,0]
	v_pk_mul_f32 v[50:51], v[50:51], v[244:245] op_sel_hi:[1,0]
	v_pk_mul_f32 v[40:41], v[40:41], v[244:245] op_sel_hi:[1,0]
	v_pk_mul_f32 v[42:43], v[42:43], v[244:245] op_sel_hi:[1,0]
	v_pk_mul_f32 v[36:37], v[36:37], v[244:245] op_sel_hi:[1,0]
	v_pk_mul_f32 v[38:39], v[38:39], v[244:245] op_sel_hi:[1,0]
	v_pk_mul_f32 v[20:21], v[20:21], v[244:245] op_sel_hi:[1,0]
	v_pk_mul_f32 v[22:23], v[22:23], v[244:245] op_sel_hi:[1,0]
	v_pk_mul_f32 v[76:77], v[76:77], v[244:245] op_sel_hi:[1,0]
	v_pk_mul_f32 v[78:79], v[78:79], v[244:245] op_sel_hi:[1,0]
